# G1 epilogue stores nontemporal (less dirty L2 data to write back at the phase barrier)
# baseline (speedup 1.0000x reference)
; __device__ __forceinline__ bf16_t f2bf(float f) { return (bf16_t)(pack2(f, 0.f) & 0xffffu); }
; __device__ __forceinline__ float siluf_(float x) { return x * __builtin_amdgcn_rcpf(1.f + __expf(-x)); }
; template <int EPI>
; __device__ __forceinline__ void gemm_tile8p(const bf16_t* __restrict__ Ag, const bf16_t* __restrict__ Bg, int K, int nt, int brow, int bcol,
;                                             char* smem, void* outp, int ldo, int nvalid, int rowoff, int rowlim) {
;     ...
; #pragma unroll
;   for (int ai = 0; ai < 2; ++ai)
; #pragma unroll
;     for (int m = 0; m < 4; ++m)
; #pragma unroll
;       for (int j = 0; j < 4; ++j) {
;         const int rl = ai * HALF + wr * 64 + m * 16 + fq * 4 + j;
;         const size_t orow = (size_t)(rowoff + rl) * ldo;
;         if (EPI == EPI_GLU) {
; #pragma unroll
;           for (int n = 0; n < 2; ++n) {
;             const int col = (bcol >> 8) * 128 + wc * 32 + n * 16 + fr;
;             const float g = acc[ai][0][m][n][j], u = acc[ai][1][m][n][j];
;             if (rl < rowlim) ((bf16_t*)outp)[orow + col] = f2bf(siluf_(g) * u);
;           }
;         } else {
; #pragma unroll
;           for (int bj = 0; bj < 2; ++bj)
; #pragma unroll
;             for (int n = 0; n < 2; ++n) {
;               const int col = bcol + bj * HALF + wc * 32 + n * 16 + fr;
;               const float v = acc[ai][bj][m][n][j];
;               if (EPI == EPI_BF16) { if (rl < rowlim && col < nvalid) ((bf16_t*)outp)[orow + col] = f2bf(v); }
;               else { if (rl < rowlim) ((float*)outp)[orow + col] = v; }
;             }
;         }
;         __builtin_amdgcn_sched_barrier(0);
;       }
.LBB0_1069:
	s_or_b64 exec, exec, s[2:3]
	s_sub_i32 s4, 0x4080, s48
	v_or_b32_e32 v160, v136, v134
	v_lshlrev_b32_e32 v160, 9, v160
	v_and_b32_e32 v161, 1, v135
	v_lshl_or_b32 v160, v161, 3, v160
	v_lshrrev_b32_e32 v161, 1, v135
	v_lshl_or_b32 v162, v133, 2, v161
	v_xor_b32_e32 v162, v162, v134
	v_lshl_add_u32 v164, v162, 4, v160
	v_xor_b32_e32 v163, 2, v162
	v_lshl_add_u32 v165, v163, 4, v160
	v_add_u32_e32 v166, 0x100, v164
	v_add_u32_e32 v167, 0x100, v165
	v_add_u32_e32 v168, 0x10000, v164
	v_add_u32_e32 v169, 0x10000, v165
	v_add_u32_e32 v170, 0x10000, v166
	v_add_u32_e32 v171, 0x10000, v167
	v_cvt_pk_bf16_f32 v176, v124, v125
	v_cvt_pk_bf16_f32 v177, v126, v127
	v_cvt_pk_bf16_f32 v178, v116, v117
	v_cvt_pk_bf16_f32 v179, v118, v119
	v_cvt_pk_bf16_f32 v180, v120, v121
	v_cvt_pk_bf16_f32 v181, v122, v123
	v_cvt_pk_bf16_f32 v182, v112, v113
	v_cvt_pk_bf16_f32 v183, v114, v115
	ds_write_b64 v164, v[176:177]
	ds_write_b64 v165, v[178:179]
	ds_write_b64 v166, v[180:181]
	ds_write_b64 v167, v[182:183]
	v_cvt_pk_bf16_f32 v184, v108, v109
	v_cvt_pk_bf16_f32 v185, v110, v111
	v_cvt_pk_bf16_f32 v186, v100, v101
	v_cvt_pk_bf16_f32 v187, v102, v103
	v_cvt_pk_bf16_f32 v188, v104, v105
	v_cvt_pk_bf16_f32 v189, v106, v107
	v_cvt_pk_bf16_f32 v190, v96, v97
	v_cvt_pk_bf16_f32 v191, v98, v99
	ds_write_b64 v166, v[184:185] offset:8192
	ds_write_b64 v167, v[186:187] offset:8192
	ds_write_b64 v164, v[188:189] offset:8192
	ds_write_b64 v165, v[190:191] offset:8192
	v_cvt_pk_bf16_f32 v176, v92, v93
	v_cvt_pk_bf16_f32 v177, v94, v95
	v_cvt_pk_bf16_f32 v178, v84, v85
	v_cvt_pk_bf16_f32 v179, v86, v87
	v_cvt_pk_bf16_f32 v180, v88, v89
	v_cvt_pk_bf16_f32 v181, v90, v91
	v_cvt_pk_bf16_f32 v182, v80, v81
	v_cvt_pk_bf16_f32 v183, v82, v83
	ds_write_b64 v164, v[176:177] offset:16384
	ds_write_b64 v165, v[178:179] offset:16384
	ds_write_b64 v166, v[180:181] offset:16384
	ds_write_b64 v167, v[182:183] offset:16384
	v_cvt_pk_bf16_f32 v184, v76, v77
	v_cvt_pk_bf16_f32 v185, v78, v79
	v_cvt_pk_bf16_f32 v186, v68, v69
	v_cvt_pk_bf16_f32 v187, v70, v71
	v_cvt_pk_bf16_f32 v188, v72, v73
	v_cvt_pk_bf16_f32 v189, v74, v75
	v_cvt_pk_bf16_f32 v190, v64, v65
	v_cvt_pk_bf16_f32 v191, v66, v67
	ds_write_b64 v166, v[184:185] offset:24576
	ds_write_b64 v167, v[186:187] offset:24576
	ds_write_b64 v164, v[188:189] offset:24576
	ds_write_b64 v165, v[190:191] offset:24576
	v_cvt_pk_bf16_f32 v176, v60, v61
	v_cvt_pk_bf16_f32 v177, v62, v63
	v_cvt_pk_bf16_f32 v178, v52, v53
	v_cvt_pk_bf16_f32 v179, v54, v55
	v_cvt_pk_bf16_f32 v180, v56, v57
	v_cvt_pk_bf16_f32 v181, v58, v59
	v_cvt_pk_bf16_f32 v182, v48, v49
	v_cvt_pk_bf16_f32 v183, v50, v51
	ds_write_b64 v168, v[176:177]
	ds_write_b64 v169, v[178:179]
	ds_write_b64 v170, v[180:181]
	ds_write_b64 v171, v[182:183]
	v_cvt_pk_bf16_f32 v184, v44, v45
	v_cvt_pk_bf16_f32 v185, v46, v47
	v_cvt_pk_bf16_f32 v186, v36, v37
	v_cvt_pk_bf16_f32 v187, v38, v39
	v_cvt_pk_bf16_f32 v188, v40, v41
	v_cvt_pk_bf16_f32 v189, v42, v43
	v_cvt_pk_bf16_f32 v190, v32, v33
	v_cvt_pk_bf16_f32 v191, v34, v35
	ds_write_b64 v170, v[184:185] offset:8192
	ds_write_b64 v171, v[186:187] offset:8192
	ds_write_b64 v168, v[188:189] offset:8192
	ds_write_b64 v169, v[190:191] offset:8192
	v_cvt_pk_bf16_f32 v176, v28, v29
	v_cvt_pk_bf16_f32 v177, v30, v31
	v_cvt_pk_bf16_f32 v178, v20, v21
	v_cvt_pk_bf16_f32 v179, v22, v23
	v_cvt_pk_bf16_f32 v180, v24, v25
	v_cvt_pk_bf16_f32 v181, v26, v27
	v_cvt_pk_bf16_f32 v182, v16, v17
	v_cvt_pk_bf16_f32 v183, v18, v19
	ds_write_b64 v168, v[176:177] offset:16384
	ds_write_b64 v169, v[178:179] offset:16384
	ds_write_b64 v170, v[180:181] offset:16384
	ds_write_b64 v171, v[182:183] offset:16384
	v_cvt_pk_bf16_f32 v184, v12, v13
	v_cvt_pk_bf16_f32 v185, v14, v15
	v_cvt_pk_bf16_f32 v186, v8, v9
	v_cvt_pk_bf16_f32 v187, v10, v11
	v_cvt_pk_bf16_f32 v188, v4, v5
	v_cvt_pk_bf16_f32 v189, v6, v7
	v_cvt_pk_bf16_f32 v190, v0, v1
	v_cvt_pk_bf16_f32 v191, v2, v3
	ds_write_b64 v170, v[184:185] offset:24576
	ds_write_b64 v171, v[186:187] offset:24576
	ds_write_b64 v168, v[188:189] offset:24576
	ds_write_b64 v169, v[190:191] offset:24576
	s_waitcnt lgkmcnt(0)
	s_barrier
; __device__ __forceinline__ bf16_t f2bf(float f) { return (bf16_t)(pack2(f, 0.f) & 0xffffu); }
; template <int EPI>
; __device__ __forceinline__ void gemm_tile8p(const bf16_t* __restrict__ Ag, const bf16_t* __restrict__ Bg, int K, int nt, int brow, int bcol,
;                                             char* smem, void* outp, int ldo, int nvalid, int rowoff, int rowlim) {
;     ...
; #pragma unroll
;           for (int bj = 0; bj < 2; ++bj)
; #pragma unroll
;             for (int n = 0; n < 2; ++n) {
;               const int col = bcol + bj * HALF + wc * 32 + n * 16 + fr;
;               const float v = acc[ai][bj][m][n][j];
;               if (EPI == EPI_BF16) { if (rl < rowlim && col < nvalid) ((bf16_t*)outp)[orow + col] = f2bf(v); }
;               else { if (rl < rowlim) ((float*)outp)[orow + col] = v; }
;             }
	v_lshrrev_b32_e32 v160, 6, v136
	v_lshl_or_b32 v160, v160, 2, v133
	v_lshlrev_b32_e32 v160, 5, v160
	v_or_b32_e32 v160, v160, v161
	v_and_b32_e32 v162, 1, v135
	v_lshl_or_b32 v162, v162, 4, v134
	v_xor_b32_e32 v163, v162, v161
	v_lshlrev_b32_e32 v164, 9, v160
	v_lshl_add_u32 v165, v162, 3, s38
	s_movk_i32 s0, 0xd08
	v_cmp_gt_i32_e64 s[40:41], s0, v165
	v_add_u32_e32 v166, s48, v160
	v_mov_b32_e32 v167, 0
	v_mov_b32_e32 v168, v165
	v_mov_b32_e32 v169, 0
	v_lshl_add_u64 v[168:169], v[168:169], 1, s[68:69]
	v_mad_u64_u32 v[168:169], vcc, v166, s72, v[168:169]
	s_mov_b32 s12, 0x3420
	s_mov_b32 s13, 0
	v_xor_b32_e32 v170, 0, v163
	v_lshl_add_u32 v170, v170, 4, v164
	ds_read_b128 v[176:179], v170 offset:0
	v_xor_b32_e32 v170, 2, v163
	v_lshl_add_u32 v170, v170, 4, v164
	ds_read_b128 v[180:183], v170 offset:1024
	v_xor_b32_e32 v170, 4, v163
	v_lshl_add_u32 v170, v170, 4, v164
	ds_read_b128 v[184:187], v170 offset:2048
	v_xor_b32_e32 v170, 6, v163
	v_lshl_add_u32 v170, v170, 4, v164
	ds_read_b128 v[188:191], v170 offset:3072
	v_add_u32_e32 v171, 0, v160
	v_cmp_gt_i32_e64 s[2:3], s4, v171
	s_waitcnt lgkmcnt(3)
	s_and_b64 exec, s[2:3], s[40:41]
	global_store_dwordx4 v[168:169], v[176:179], off nt
	s_mov_b64 exec, -1
	v_lshl_add_u64 v[168:169], v[168:169], 0, s[12:13]
	v_add_u32_e32 v171, 2, v160
	v_cmp_gt_i32_e64 s[2:3], s4, v171
	s_waitcnt lgkmcnt(2)
	s_and_b64 exec, s[2:3], s[40:41]
	global_store_dwordx4 v[168:169], v[180:183], off nt
	s_mov_b64 exec, -1
	v_lshl_add_u64 v[168:169], v[168:169], 0, s[12:13]
	v_add_u32_e32 v171, 4, v160
	v_cmp_gt_i32_e64 s[2:3], s4, v171
	s_waitcnt lgkmcnt(1)
	s_and_b64 exec, s[2:3], s[40:41]
	global_store_dwordx4 v[168:169], v[184:187], off nt
	s_mov_b64 exec, -1
	v_lshl_add_u64 v[168:169], v[168:169], 0, s[12:13]
	v_add_u32_e32 v171, 6, v160
	v_cmp_gt_i32_e64 s[2:3], s4, v171
	s_waitcnt lgkmcnt(0)
	s_and_b64 exec, s[2:3], s[40:41]
	global_store_dwordx4 v[168:169], v[188:191], off nt
	s_mov_b64 exec, -1
	v_lshl_add_u64 v[168:169], v[168:169], 0, s[12:13]
	v_xor_b32_e32 v170, 8, v163
	v_lshl_add_u32 v170, v170, 4, v164
	ds_read_b128 v[176:179], v170 offset:4096
	v_xor_b32_e32 v170, 10, v163
	v_lshl_add_u32 v170, v170, 4, v164
	ds_read_b128 v[180:183], v170 offset:5120
	v_xor_b32_e32 v170, 12, v163
	v_lshl_add_u32 v170, v170, 4, v164
	ds_read_b128 v[184:187], v170 offset:6144
	v_xor_b32_e32 v170, 14, v163
	v_lshl_add_u32 v170, v170, 4, v164
	ds_read_b128 v[188:191], v170 offset:7168
	v_add_u32_e32 v171, 8, v160
	v_cmp_gt_i32_e64 s[2:3], s4, v171
	s_waitcnt lgkmcnt(3)
	s_and_b64 exec, s[2:3], s[40:41]
	global_store_dwordx4 v[168:169], v[176:179], off nt
	s_mov_b64 exec, -1
	v_lshl_add_u64 v[168:169], v[168:169], 0, s[12:13]
	v_add_u32_e32 v171, 10, v160
	v_cmp_gt_i32_e64 s[2:3], s4, v171
	s_waitcnt lgkmcnt(2)
	s_and_b64 exec, s[2:3], s[40:41]
	global_store_dwordx4 v[168:169], v[180:183], off nt
	s_mov_b64 exec, -1
	v_lshl_add_u64 v[168:169], v[168:169], 0, s[12:13]
	v_add_u32_e32 v171, 12, v160
	v_cmp_gt_i32_e64 s[2:3], s4, v171
	s_waitcnt lgkmcnt(1)
	s_and_b64 exec, s[2:3], s[40:41]
	global_store_dwordx4 v[168:169], v[184:187], off nt
	s_mov_b64 exec, -1
	v_lshl_add_u64 v[168:169], v[168:169], 0, s[12:13]
	v_add_u32_e32 v171, 14, v160
	v_cmp_gt_i32_e64 s[2:3], s4, v171
	s_waitcnt lgkmcnt(0)
	s_and_b64 exec, s[2:3], s[40:41]
	global_store_dwordx4 v[168:169], v[188:191], off nt
	s_mov_b64 exec, -1
	v_lshl_add_u64 v[168:169], v[168:169], 0, s[12:13]
	v_xor_b32_e32 v170, 16, v163
	v_lshl_add_u32 v170, v170, 4, v164
	ds_read_b128 v[176:179], v170 offset:8192
	v_xor_b32_e32 v170, 18, v163
	v_lshl_add_u32 v170, v170, 4, v164
	ds_read_b128 v[180:183], v170 offset:9216
	v_xor_b32_e32 v170, 20, v163
	v_lshl_add_u32 v170, v170, 4, v164
	ds_read_b128 v[184:187], v170 offset:10240
	v_xor_b32_e32 v170, 22, v163
	v_lshl_add_u32 v170, v170, 4, v164
	ds_read_b128 v[188:191], v170 offset:11264
	v_add_u32_e32 v171, 16, v160
	v_cmp_gt_i32_e64 s[2:3], s4, v171
	s_waitcnt lgkmcnt(3)
	s_and_b64 exec, s[2:3], s[40:41]
	global_store_dwordx4 v[168:169], v[176:179], off nt
	s_mov_b64 exec, -1
	v_lshl_add_u64 v[168:169], v[168:169], 0, s[12:13]
	v_add_u32_e32 v171, 18, v160
	v_cmp_gt_i32_e64 s[2:3], s4, v171
	s_waitcnt lgkmcnt(2)
	s_and_b64 exec, s[2:3], s[40:41]
	global_store_dwordx4 v[168:169], v[180:183], off nt
	s_mov_b64 exec, -1
	v_lshl_add_u64 v[168:169], v[168:169], 0, s[12:13]
	v_add_u32_e32 v171, 20, v160
	v_cmp_gt_i32_e64 s[2:3], s4, v171
	s_waitcnt lgkmcnt(1)
	s_and_b64 exec, s[2:3], s[40:41]
	global_store_dwordx4 v[168:169], v[184:187], off nt
	s_mov_b64 exec, -1
	v_lshl_add_u64 v[168:169], v[168:169], 0, s[12:13]
	v_add_u32_e32 v171, 22, v160
	v_cmp_gt_i32_e64 s[2:3], s4, v171
	s_waitcnt lgkmcnt(0)
	s_and_b64 exec, s[2:3], s[40:41]
	global_store_dwordx4 v[168:169], v[188:191], off nt
	s_mov_b64 exec, -1
	v_lshl_add_u64 v[168:169], v[168:169], 0, s[12:13]
	v_xor_b32_e32 v170, 24, v163
	v_lshl_add_u32 v170, v170, 4, v164
	ds_read_b128 v[176:179], v170 offset:12288
	v_xor_b32_e32 v170, 26, v163
	v_lshl_add_u32 v170, v170, 4, v164
	ds_read_b128 v[180:183], v170 offset:13312
	v_xor_b32_e32 v170, 28, v163
	v_lshl_add_u32 v170, v170, 4, v164
	ds_read_b128 v[184:187], v170 offset:14336
	v_xor_b32_e32 v170, 30, v163
	v_lshl_add_u32 v170, v170, 4, v164
	ds_read_b128 v[188:191], v170 offset:15360
	v_add_u32_e32 v171, 24, v160
	v_cmp_gt_i32_e64 s[2:3], s4, v171
	s_waitcnt lgkmcnt(3)
	s_and_b64 exec, s[2:3], s[40:41]
	global_store_dwordx4 v[168:169], v[176:179], off nt
	s_mov_b64 exec, -1
	v_lshl_add_u64 v[168:169], v[168:169], 0, s[12:13]
	v_add_u32_e32 v171, 26, v160
	v_cmp_gt_i32_e64 s[2:3], s4, v171
	s_waitcnt lgkmcnt(2)
	s_and_b64 exec, s[2:3], s[40:41]
	global_store_dwordx4 v[168:169], v[180:183], off nt
	s_mov_b64 exec, -1
	v_lshl_add_u64 v[168:169], v[168:169], 0, s[12:13]
	v_add_u32_e32 v171, 28, v160
	v_cmp_gt_i32_e64 s[2:3], s4, v171
	s_waitcnt lgkmcnt(1)
	s_and_b64 exec, s[2:3], s[40:41]
	global_store_dwordx4 v[168:169], v[184:187], off nt
	s_mov_b64 exec, -1
	v_lshl_add_u64 v[168:169], v[168:169], 0, s[12:13]
	v_add_u32_e32 v171, 30, v160
	v_cmp_gt_i32_e64 s[2:3], s4, v171
	s_waitcnt lgkmcnt(0)
	s_and_b64 exec, s[2:3], s[40:41]
	global_store_dwordx4 v[168:169], v[188:191], off nt
	s_mov_b64 exec, -1
	v_lshl_add_u64 v[168:169], v[168:169], 0, s[12:13]
	s_branch .LBB0_1060
